# slot rebalance: WIN/WBR of next layer moved from phase-1 slot to phase-10 slot (P1 slot 3136 tiles, P10 slot 3880 tiles), phase 0 only for layer 0
# baseline (speedup 1.0000x reference)
; #define PH_BEGIN const int zi = opaque0(); unsigned char* ws = P.ws + zi; float* const OUT = P.out + zi; (void)OUT; const int tid = opqv((int)threadIdx.x); const int bid = opqs((int)blockIdx.x); const int G = opqs((int)gridDim.x); (void)tid; (void)bid; (void)G; unsigned char* WB = ws + WS_WB; float* SS = (float*)(ws + WS_SS); (void)WB; (void)SS; (void)zi;
; __global__ void __launch_bounds__(512) mega(Params P) {
;     ...
;             { PH_BEGIN convT_w<2>(INP(7) + (size_t)l * D * 6928, 6928, 0, INP(5) + (size_t)l * D, (bf16_t*)(WB + WB_WIN), D, D, 4096, bid * 8 + (tid >> 6), G * 8, tid & 63, 2112); }
.LBB0_695:
	s_and_b32 s2, s2, 0xffff
	s_mov_b32 s3, s101
	s_cmp_eq_u32 s100, 1
	s_cbranch_scc0 .Lh695_done
	s_or_b32 s2, s2, 0x10000
	s_mov_b32 s3, 0x100000

; #define PH_BEGIN const int zi = opaque0(); unsigned char* ws = P.ws + zi; float* const OUT = P.out + zi; (void)OUT; const int tid = opqv((int)threadIdx.x); const int bid = opqs((int)blockIdx.x); const int G = opqs((int)gridDim.x); (void)tid; (void)bid; (void)G; unsigned char* WB = ws + WS_WB; float* SS = (float*)(ws + WS_SS); (void)WB; (void)SS; (void)zi;
; __global__ void __launch_bounds__(512) mega(Params P) {
;     ...
;             { PH_BEGIN convT_w<0>(INP(7) + (size_t)l * D * 6928, 6928, 3856, INP(5) + (size_t)l * D, (bf16_t*)(WB + WB_WG), D, D, 3072, bid * 8 + (tid >> 6), G * 8, tid & 63, 3136); }
.LBB0_701:
	s_or_b32 s2, s2, 0x10000
	s_mov_b32 s3, 0x100000
	s_cmp_eq_u32 s100, 1
	s_cbranch_scc0 .Lh701_done
	s_and_b32 s2, s2, 0xffff
	s_mov_b32 s3, s101
